# s1 item order reversed for workgroups with bit 3 of their index set (GLA, GLA, HGRN, HGRN, attention)
# baseline (speedup 1.0000x reference)
.LBB0_180:
	s_andn2_b64 vcc, exec, s[2:3]
	s_cbranch_vccnz .LBB0_305
	s_cmpk_gt_i32 s20, 0x4ff
	s_cbranch_scc1 .LBB0_305
	s_ashr_i32 s25, s24, 31
	s_lshl_b64 s[2:3], s[24:25], 13
	s_add_u32 s82, s48, s2
	s_addc_u32 s83, s49, s3
	s_lshl_b32 s8, s24, 7
	s_cmp_gt_i32 s70, 7
	s_cselect_b64 s[30:31], -1, 0
	s_lshl_b32 s9, s20, 3
	s_lshl_b32 s10, s72, 3
	s_mov_b32 s100, s72
	s_mov_b32 s101, s10
	s_cmp_lg_u32 s34, 0x100
	s_cbranch_scc1 .Lrev_skip
	s_bitcmp1_b32 s20, 3
	s_cbranch_scc0 .Lrev_skip
	s_lshl_b32 s100, s72, 2
	s_add_i32 s20, s20, s100
	s_lshl_b32 s9, s20, 3
	s_sub_i32 s100, 0, s72
	s_sub_i32 s101, 0, s10
.Lrev_skip:
	s_branch .LBB0_190
.LBB0_183:
	s_or_b64 exec, exec, s[38:39]
	s_add_i32 s2, s2, s72
	s_cmpk_gt_i32 s2, 0xbf
	s_cbranch_scc1 .LBB0_179

.LBB0_189:
	s_add_i32 s20, s20, s100
	s_add_i32 s9, s9, s101
	s_cmpk_gt_u32 s20, 0x4ff
	s_cbranch_scc1 .LBB0_305
